# G1-even too: second half-tile's rowss+bias prefetched during first half's epilogue
# speedup vs baseline: 1.0754x; 1.0001x over previous
.LBB0_308:
	s_or_b64 exec, exec, s[54:55]
	v_mov_b32_e32 v210, 64
	v_xor_b32_e32 v211, 32, v209
	v_xor_b32_e32 v212, 16, v209
	v_xor_b32_e32 v213, 8, v209
	v_xor_b32_e32 v214, 4, v209
	v_xor_b32_e32 v215, 2, v209
	v_xor_b32_e32 v216, 1, v209
	v_mov_b32_e32 v217, 2
	v_bfrev_b32_e32 v218, 32
	v_bfrev_b32_e32 v219, 64
	v_mov_b32_e32 v220, 0xff800000
	v_mov_b32_e32 v221, 0x80
	v_mov_b32_e32 v222, 0x200
	v_mov_b32_e32 v223, 0x2000
	v_mov_b32_e32 v224, 0x461c4000
	v_mov_b32_e32 v225, 0x63
	s_add_i32 s76, s76, s48
	s_cmp_ge_i32 s76, s4
	s_cbranch_scc1 .LBB0_423

.LBB0_314:
	s_barrier
	s_waitcnt vmcnt(9)
	ds_write_b128 v186, v[142:145]
	ds_write_b128 v186, v[134:137] offset:4608
	ds_write_b128 v186, v[130:133] offset:9216
	s_waitcnt vmcnt(7)
	ds_write_b128 v186, v[146:149] offset:13824
	ds_write_b128 v186, v[138:141] offset:18432
	s_waitcnt vmcnt(6)
	ds_write_b128 v186, v[150:153] offset:23040
	s_waitcnt vmcnt(5)
	ds_write_b128 v186, v[154:157] offset:27648
	s_waitcnt vmcnt(4)
	ds_write_b128 v186, v[158:161] offset:32256
	s_waitcnt vmcnt(3)
	ds_write_b128 v186, v[162:165] offset:36864
	s_waitcnt vmcnt(2)
	ds_write_b128 v186, v[166:169] offset:41472
	s_waitcnt vmcnt(1)
	ds_write_b128 v186, v[170:173] offset:46080
	s_waitcnt vmcnt(0)
	ds_write_b128 v186, v[174:177] offset:50688
	s_waitcnt lgkmcnt(0)
	s_barrier
	s_setprio 2
	s_mov_b32 vcc_hi, 0
	ds_read_b128 v[244:247], v229
	ds_read_b128 v[210:213], v230 offset:18432
	ds_read_b128 v[248:251], v229 offset:4608
	ds_read_b128 v[214:217], v230 offset:23040
	ds_read_b128 v[218:221], v230 offset:27648
	ds_read_b128 v[222:225], v230 offset:32256
	s_waitcnt lgkmcnt(4)
	v_mfma_f32_32x32x16_bf16 v[114:129], v[210:213], v[244:247], v[114:129]
	s_add_u32 vcc_lo, s22, 0xd400080
	v_lshl_add_u64 v[240:241], v[202:203], 0, vcc
	global_load_dwordx4 v[142:145], v[240:241], off
	ds_read_b128 v[252:255], v229 offset:32
	s_waitcnt lgkmcnt(4)
	v_mfma_f32_32x32x16_bf16 v[98:113], v[210:213], v[248:251], v[98:113]
	s_add_u32 vcc_lo, s22, 0xd410080
	v_lshl_add_u64 v[178:179], v[202:203], 0, vcc
	global_load_dwordx4 v[134:137], v[178:179], off
	ds_read_b128 v[210:213], v230 offset:18464
	s_waitcnt lgkmcnt(4)
	v_mfma_f32_32x32x16_bf16 v[82:97], v[214:217], v[244:247], v[82:97]
	s_add_u32 vcc_lo, s22, 0xd420080
	v_lshl_add_u64 v[240:241], v[202:203], 0, vcc
	global_load_dwordx4 v[130:133], v[240:241], off
	ds_read_b128 v[232:235], v229 offset:4640
	v_mfma_f32_32x32x16_bf16 v[66:81], v[214:217], v[248:251], v[66:81]
	s_add_u32 vcc_lo, s22, 0xd430080
	v_lshl_add_u64 v[178:179], v[202:203], 0, vcc
	global_load_dwordx4 v[146:149], v[178:179], off
	ds_read_b128 v[214:217], v230 offset:23072
	s_waitcnt lgkmcnt(5)
	v_mfma_f32_32x32x16_bf16 v[50:65], v[218:221], v[244:247], v[50:65]
	s_add_u32 vcc_lo, s22, 0xa000080
	v_lshl_add_u64 v[240:241], v[200:201], 0, vcc
	global_load_dwordx4 v[138:141], v[240:241], off
	v_mfma_f32_32x32x16_bf16 v[34:49], v[218:221], v[248:251], v[34:49]
	s_add_u32 vcc_lo, s22, 0xa010080
	v_lshl_add_u64 v[178:179], v[200:201], 0, vcc
	global_load_dwordx4 v[150:153], v[178:179], off
	ds_read_b128 v[218:221], v230 offset:27680
	s_waitcnt lgkmcnt(5)
	v_mfma_f32_32x32x16_bf16 v[18:33], v[222:225], v[244:247], v[18:33]
	s_add_u32 vcc_lo, s22, 0xa020080
	v_lshl_add_u64 v[240:241], v[200:201], 0, vcc
	global_load_dwordx4 v[154:157], v[240:241], off
	v_mfma_f32_32x32x16_bf16 v[2:17], v[222:225], v[248:251], v[2:17]
	s_add_u32 vcc_lo, s22, 0xa030080
	v_lshl_add_u64 v[178:179], v[200:201], 0, vcc
	global_load_dwordx4 v[158:161], v[178:179], off
	ds_read_b128 v[222:225], v230 offset:32288
	s_waitcnt lgkmcnt(4)
	v_mfma_f32_32x32x16_bf16 v[114:129], v[210:213], v[252:255], v[114:129]
	s_add_u32 vcc_lo, s22, 0xa040080
	v_lshl_add_u64 v[240:241], v[200:201], 0, vcc
	global_load_dwordx4 v[162:165], v[240:241], off
	ds_read_b128 v[244:247], v229 offset:64
	s_waitcnt lgkmcnt(4)
	v_mfma_f32_32x32x16_bf16 v[98:113], v[210:213], v[232:235], v[98:113]
	s_add_u32 vcc_lo, s22, 0xa050080
	v_lshl_add_u64 v[178:179], v[200:201], 0, vcc
	global_load_dwordx4 v[166:169], v[178:179], off
	ds_read_b128 v[210:213], v230 offset:18496
	s_waitcnt lgkmcnt(4)
	v_mfma_f32_32x32x16_bf16 v[82:97], v[214:217], v[252:255], v[82:97]
	s_add_u32 vcc_lo, s22, 0xa060080
	v_lshl_add_u64 v[240:241], v[200:201], 0, vcc
	global_load_dwordx4 v[170:173], v[240:241], off
	ds_read_b128 v[248:251], v229 offset:4672
	v_mfma_f32_32x32x16_bf16 v[66:81], v[214:217], v[232:235], v[66:81]
	s_add_u32 vcc_lo, s22, 0xa070080
	v_lshl_add_u64 v[178:179], v[200:201], 0, vcc
	global_load_dwordx4 v[174:177], v[178:179], off
	ds_read_b128 v[214:217], v230 offset:23104
	s_waitcnt lgkmcnt(5)
	v_mfma_f32_32x32x16_bf16 v[50:65], v[218:221], v[252:255], v[50:65]
	v_mfma_f32_32x32x16_bf16 v[34:49], v[218:221], v[232:235], v[34:49]
	ds_read_b128 v[218:221], v230 offset:27712
	s_waitcnt lgkmcnt(5)
	v_mfma_f32_32x32x16_bf16 v[18:33], v[222:225], v[252:255], v[18:33]
	v_mfma_f32_32x32x16_bf16 v[2:17], v[222:225], v[232:235], v[2:17]
	ds_read_b128 v[222:225], v230 offset:32320
	s_waitcnt lgkmcnt(4)
	v_mfma_f32_32x32x16_bf16 v[114:129], v[210:213], v[244:247], v[114:129]
	ds_read_b128 v[252:255], v229 offset:96
	s_waitcnt lgkmcnt(4)
	v_mfma_f32_32x32x16_bf16 v[98:113], v[210:213], v[248:251], v[98:113]
	ds_read_b128 v[210:213], v230 offset:18528
	s_waitcnt lgkmcnt(4)
	v_mfma_f32_32x32x16_bf16 v[82:97], v[214:217], v[244:247], v[82:97]
	ds_read_b128 v[232:235], v229 offset:4704
	v_mfma_f32_32x32x16_bf16 v[66:81], v[214:217], v[248:251], v[66:81]
	ds_read_b128 v[214:217], v230 offset:23136
	s_waitcnt lgkmcnt(5)
	v_mfma_f32_32x32x16_bf16 v[50:65], v[218:221], v[244:247], v[50:65]
	v_mfma_f32_32x32x16_bf16 v[34:49], v[218:221], v[248:251], v[34:49]
	ds_read_b128 v[218:221], v230 offset:27744
	s_waitcnt lgkmcnt(5)
	v_mfma_f32_32x32x16_bf16 v[18:33], v[222:225], v[244:247], v[18:33]
	v_mfma_f32_32x32x16_bf16 v[2:17], v[222:225], v[248:251], v[2:17]
	ds_read_b128 v[222:225], v230 offset:32352
	s_waitcnt lgkmcnt(4)
	v_mfma_f32_32x32x16_bf16 v[114:129], v[210:213], v[252:255], v[114:129]
	s_waitcnt lgkmcnt(3)
	v_mfma_f32_32x32x16_bf16 v[98:113], v[210:213], v[232:235], v[98:113]
	s_waitcnt lgkmcnt(2)
	v_mfma_f32_32x32x16_bf16 v[82:97], v[214:217], v[252:255], v[82:97]
	v_mfma_f32_32x32x16_bf16 v[66:81], v[214:217], v[232:235], v[66:81]
	s_waitcnt lgkmcnt(1)
	v_mfma_f32_32x32x16_bf16 v[50:65], v[218:221], v[252:255], v[50:65]
	v_mfma_f32_32x32x16_bf16 v[34:49], v[218:221], v[232:235], v[34:49]
	s_waitcnt lgkmcnt(0)
	v_mfma_f32_32x32x16_bf16 v[18:33], v[222:225], v[252:255], v[18:33]
	v_mfma_f32_32x32x16_bf16 v[2:17], v[222:225], v[232:235], v[2:17]
	s_setprio 0
	s_add_u32 s22, s22, 0x80
	s_addc_u32 s23, s23, 0
	s_cmpk_eq_i32 s22, 0x780
	s_cbranch_scc0 .LBB0_314
	v_mov_b32_e32 v210, 64
	v_xor_b32_e32 v211, 32, v209
	v_xor_b32_e32 v212, 16, v209
	v_xor_b32_e32 v213, 8, v209
	v_xor_b32_e32 v214, 4, v209
	v_xor_b32_e32 v215, 2, v209
	v_xor_b32_e32 v216, 1, v209
	v_mov_b32_e32 v217, 2
	v_bfrev_b32_e32 v218, 32
	v_bfrev_b32_e32 v219, 64
	v_mov_b32_e32 v220, 0xff800000
	v_mov_b32_e32 v221, 0x80
	v_mov_b32_e32 v222, 0x200
	v_mov_b32_e32 v223, 0x2000
	v_mov_b32_e32 v224, 0x461c4000
	v_mov_b32_e32 v225, 0x63
	v_mov_b64_e32 v[178:179], 0xf500000
	s_setprio 0
	s_barrier
	s_waitcnt vmcnt(11)
	ds_write_b128 v186, v[142:145]
	s_waitcnt vmcnt(10)
	ds_write_b128 v186, v[134:137] offset:4608
	s_waitcnt vmcnt(9)
	ds_write_b128 v186, v[130:133] offset:9216
	s_waitcnt vmcnt(8)
	ds_write_b128 v186, v[146:149] offset:13824
	s_waitcnt vmcnt(7)
	ds_write_b128 v186, v[138:141] offset:18432
	s_waitcnt vmcnt(6)
	ds_write_b128 v186, v[150:153] offset:23040
	s_waitcnt vmcnt(5)
	ds_write_b128 v186, v[154:157] offset:27648
	s_waitcnt vmcnt(4)
	ds_write_b128 v186, v[158:161] offset:32256
	s_waitcnt vmcnt(3)
	ds_write_b128 v186, v[162:165] offset:36864
	s_waitcnt vmcnt(2)
	ds_write_b128 v186, v[166:169] offset:41472
	s_waitcnt vmcnt(1)
	ds_write_b128 v186, v[170:173] offset:46080
	s_waitcnt vmcnt(0)
	ds_write_b128 v186, v[174:177] offset:50688
	s_waitcnt lgkmcnt(0)
	s_setprio 0
	s_barrier
	s_setprio 1
	ds_read_b128 v[130:133], v230 offset:18432
	ds_read_b128 v[134:137], v229
	ds_read_b128 v[138:141], v229 offset:32
	ds_read_b128 v[142:145], v230 offset:18464
	ds_read_b128 v[146:149], v229 offset:4608
	ds_read_b128 v[150:153], v229 offset:4640
	s_waitcnt lgkmcnt(4)
	v_mfma_f32_32x32x16_bf16 v[114:129], v[130:133], v[134:137], v[114:129]
	v_add_u32_e32 v170, s2, v187
	v_or_b32_e32 v168, s3, v204
	v_ashrrev_i32_e32 v172, 11, v170
	v_ashrrev_i32_e32 v173, 6, v168
	v_lshlrev_b32_e32 v174, 12, v172
	v_or_b32_e32 v166, v170, v189
	v_and_b32_e32 v200, 0x7c0, v170
	s_waitcnt lgkmcnt(1)
	v_mfma_f32_32x32x16_bf16 v[98:113], v[130:133], v[146:149], v[98:113]
	ds_read_b128 v[130:133], v230 offset:23040
	ds_read_b128 v[154:157], v230 offset:23072
	v_cmp_gt_i32_e32 vcc, 47, v173
	v_ashrrev_i32_e32 v169, 31, v168
	v_ashrrev_i32_e32 v175, 31, v174
	v_ashrrev_i32_e32 v167, 31, v166
	v_lshlrev_b32_e32 v0, 2, v188
	s_waitcnt lgkmcnt(1)
	v_mfma_f32_32x32x16_bf16 v[82:97], v[130:133], v[134:137], v[82:97]
	v_mfma_f32_32x32x16_bf16 v[66:81], v[130:133], v[146:149], v[66:81]
	ds_read_b128 v[130:133], v230 offset:27648
	ds_read_b128 v[158:161], v230 offset:27680
	s_waitcnt lgkmcnt(1)
	v_mfma_f32_32x32x16_bf16 v[50:65], v[130:133], v[134:137], v[50:65]
	v_mfma_f32_32x32x16_bf16 v[34:49], v[130:133], v[146:149], v[34:49]
	ds_read_b128 v[130:133], v230 offset:32256
	ds_read_b128 v[162:165], v230 offset:32288
	s_waitcnt lgkmcnt(1)
	v_mfma_f32_32x32x16_bf16 v[18:33], v[130:133], v[134:137], v[18:33]
	v_mfma_f32_32x32x16_bf16 v[2:17], v[130:133], v[146:149], v[2:17]
	v_mfma_f32_32x32x16_bf16 v[114:129], v[142:145], v[138:141], v[114:129]
	v_mfma_f32_32x32x16_bf16 v[98:113], v[142:145], v[150:153], v[98:113]
	v_mfma_f32_32x32x16_bf16 v[82:97], v[154:157], v[138:141], v[82:97]
	v_mfma_f32_32x32x16_bf16 v[66:81], v[154:157], v[150:153], v[66:81]
	v_mfma_f32_32x32x16_bf16 v[50:65], v[158:161], v[138:141], v[50:65]
	v_mfma_f32_32x32x16_bf16 v[34:49], v[158:161], v[150:153], v[34:49]
	s_waitcnt lgkmcnt(0)
	v_mfma_f32_32x32x16_bf16 v[18:33], v[162:165], v[138:141], v[18:33]
	ds_read_b128 v[130:133], v230 offset:18496
	ds_read_b128 v[134:137], v229 offset:64
	ds_read_b128 v[138:141], v229 offset:96
	ds_read_b128 v[142:145], v230 offset:18528
	v_mfma_f32_32x32x16_bf16 v[2:17], v[162:165], v[150:153], v[2:17]
	ds_read_b128 v[146:149], v229 offset:4672
	ds_read_b128 v[150:153], v229 offset:4704
	s_waitcnt lgkmcnt(4)
	v_mfma_f32_32x32x16_bf16 v[114:129], v[130:133], v[134:137], v[114:129]
	s_waitcnt lgkmcnt(1)
	v_mfma_f32_32x32x16_bf16 v[98:113], v[130:133], v[146:149], v[98:113]
	ds_read_b128 v[130:133], v230 offset:23104
	ds_read_b128 v[154:157], v230 offset:23136
	s_waitcnt lgkmcnt(1)
	v_mfma_f32_32x32x16_bf16 v[82:97], v[130:133], v[134:137], v[82:97]
	v_mfma_f32_32x32x16_bf16 v[66:81], v[130:133], v[146:149], v[66:81]
	ds_read_b128 v[130:133], v230 offset:27712
	ds_read_b128 v[158:161], v230 offset:27744
	s_waitcnt lgkmcnt(1)
	v_mfma_f32_32x32x16_bf16 v[50:65], v[130:133], v[134:137], v[50:65]
	v_mfma_f32_32x32x16_bf16 v[34:49], v[130:133], v[146:149], v[34:49]
	ds_read_b128 v[130:133], v230 offset:32320
	ds_read_b128 v[162:165], v230 offset:32352
	s_waitcnt lgkmcnt(0)
	s_setprio 0
	s_barrier
	v_mfma_f32_32x32x16_bf16 v[18:33], v[130:133], v[134:137], v[18:33]
	v_mfma_f32_32x32x16_bf16 v[2:17], v[130:133], v[146:149], v[2:17]
	v_mfma_f32_32x32x16_bf16 v[114:129], v[142:145], v[138:141], v[114:129]
	v_mfma_f32_32x32x16_bf16 v[98:113], v[142:145], v[150:153], v[98:113]
	v_mfma_f32_32x32x16_bf16 v[82:97], v[154:157], v[138:141], v[82:97]
	v_mfma_f32_32x32x16_bf16 v[66:81], v[154:157], v[150:153], v[66:81]
	v_mfma_f32_32x32x16_bf16 v[50:65], v[158:161], v[138:141], v[50:65]
	v_mfma_f32_32x32x16_bf16 v[34:49], v[158:161], v[150:153], v[34:49]
	v_mfma_f32_32x32x16_bf16 v[18:33], v[162:165], v[138:141], v[18:33]
	v_mfma_f32_32x32x16_bf16 v[2:17], v[162:165], v[150:153], v[2:17]
	s_and_saveexec_b64 s[54:55], vcc
	s_cbranch_execz .LBB0_370
	v_lshl_add_u64 v[130:131], v[174:175], 2, s[42:43]
	v_lshl_add_u64 v[130:131], v[168:169], 2, v[130:131]
	v_lshl_add_u64 v[132:133], v[166:167], 2, s[40:41]
	v_lshl_add_u64 v[130:131], v[130:131], 0, v[0:1]
	global_load_dword v234, v[132:133], off
	global_load_dword v235, v[132:133], off offset:128
	global_load_dwordx4 v[244:247], v[130:131], off offset:256
	global_load_dwordx4 v[248:251], v[130:131], off offset:288
	global_load_dwordx4 v[252:255], v[130:131], off offset:320
	global_load_dwordx4 v[236:239], v[130:131], off offset:352
	global_load_dwordx4 v[210:213], v[130:131], off offset:384
	global_load_dwordx4 v[214:217], v[130:131], off offset:416
	global_load_dwordx4 v[218:221], v[130:131], off offset:448
	global_load_dwordx4 v[222:225], v[130:131], off offset:480
	global_load_dword v163, v[132:133], off
	global_load_dword v162, v[132:133], off offset:128
	global_load_dwordx4 v[158:161], v[130:131], off
	global_load_dwordx4 v[154:157], v[130:131], off offset:32
	global_load_dwordx4 v[150:153], v[130:131], off offset:64
	global_load_dwordx4 v[146:149], v[130:131], off offset:96
	global_load_dwordx4 v[142:145], v[130:131], off offset:128
	global_load_dwordx4 v[138:141], v[130:131], off offset:160
	global_load_dwordx4 v[134:137], v[130:131], off offset:192
	s_nop 0
	global_load_dwordx4 v[130:133], v[130:131], off offset:224
	v_cmp_lt_i32_e32 vcc, 7, v173
	s_and_saveexec_b64 s[2:3], vcc
	s_xor_b64 s[60:61], exec, s[2:3]
	s_cbranch_execz .LBB0_356
	s_movk_i32 s2, 0x200
	v_cmp_ne_u32_e32 vcc, s2, v168
	s_and_saveexec_b64 s[2:3], vcc
	s_xor_b64 s[2:3], exec, s[2:3]
	s_cbranch_execz .LBB0_353
	v_cmp_lt_u32_e32 vcc, 17, v173
	s_and_saveexec_b64 s[6:7], vcc
	s_xor_b64 s[62:63], exec, s[6:7]
	s_cbranch_execz .LBB0_350
	v_cmp_lt_u32_e32 vcc, 25, v173
	s_and_saveexec_b64 s[6:7], vcc
	s_xor_b64 s[64:65], exec, s[6:7]
	s_cbranch_execz .LBB0_347
	v_cmp_lt_u32_e32 vcc, 27, v173
	s_and_saveexec_b64 s[6:7], vcc
	s_xor_b64 s[66:67], exec, s[6:7]
	s_cbranch_execz .LBB0_344
	v_cmp_lt_u32_e32 vcc, 29, v173
	s_and_saveexec_b64 s[6:7], vcc
	s_xor_b64 s[68:69], exec, s[6:7]
	s_cbranch_execz .LBB0_341
	v_cmp_lt_u32_e32 vcc, 31, v173
	s_and_saveexec_b64 s[6:7], vcc
	s_xor_b64 s[70:71], exec, s[6:7]
	s_cbranch_execz .LBB0_338
	v_cmp_lt_u32_e32 vcc, 33, v173
	s_and_saveexec_b64 s[6:7], vcc
	s_xor_b64 s[72:73], exec, s[6:7]
	s_cbranch_execz .LBB0_335
	v_cmp_lt_u32_e32 vcc, 35, v173
	s_and_saveexec_b64 s[6:7], vcc
	s_xor_b64 s[58:59], exec, s[6:7]
	s_cbranch_execz .LBB0_332
	v_cmp_lt_u32_e32 vcc, 37, v173
	s_and_saveexec_b64 s[6:7], vcc
	s_xor_b64 s[22:23], exec, s[6:7]
	s_cbranch_execz .LBB0_329
	s_movk_i32 s6, 0xb80
	v_cmp_ne_u32_e32 vcc, s6, v168
	v_mov_b32_e32 v171, 0
	v_mov_b64_e32 v[176:177], 0
	s_mov_b64 s[56:57], 0
	s_and_saveexec_b64 s[74:75], vcc
	s_cbranch_execz .LBB0_328
	v_ashrrev_i32_e32 v171, 31, v170
	v_lshlrev_b64 v[164:165], 10, v[170:171]
	v_lshl_add_u64 v[164:165], s[38:39], 0, v[164:165]
	v_mov_b32_e32 v176, v168
	v_mov_b32_e32 v177, v1
	v_lshl_add_u64 v[164:165], v[176:177], 1, v[164:165]
	s_mov_b64 s[6:7], 0x4ffed00
	s_mov_b64 s[56:57], exec
	v_lshl_add_u64 v[176:177], v[164:165], 0, s[6:7]
	v_mov_b32_e32 v171, 0x200

.LBB0_370:
	s_or_b64 exec, exec, s[54:55]
	s_nop 2
	v_or_b32_e32 v100, 1, v173
	v_cmp_gt_i32_e32 vcc, 47, v100
	s_and_saveexec_b64 s[54:55], vcc
	s_cbranch_execz .LBB0_308
	v_lshl_add_u64 v[66:67], v[174:175], 2, s[42:43]
	v_lshl_add_u64 v[66:67], v[168:169], 2, v[66:67]
	v_lshl_add_u64 v[68:69], v[166:167], 2, s[40:41]
	v_lshl_add_u64 v[66:67], v[66:67], 0, v[0:1]
	s_waitcnt vmcnt(8)
	v_mov_b32_e32 v99, v234
	v_mov_b32_e32 v98, v235
	v_mov_b32_e32 v94, v244
	v_mov_b32_e32 v95, v245
	v_mov_b32_e32 v96, v246
	v_mov_b32_e32 v97, v247
	v_mov_b32_e32 v90, v248
	v_mov_b32_e32 v91, v249
	v_mov_b32_e32 v92, v250
	v_mov_b32_e32 v93, v251
	v_mov_b32_e32 v86, v252
	v_mov_b32_e32 v87, v253
	v_mov_b32_e32 v88, v254
	v_mov_b32_e32 v89, v255
	v_mov_b32_e32 v82, v236
	v_mov_b32_e32 v83, v237
	v_mov_b32_e32 v84, v238
	v_mov_b32_e32 v85, v239
	v_mov_b32_e32 v78, v210
	v_mov_b32_e32 v79, v211
	v_mov_b32_e32 v80, v212
	v_mov_b32_e32 v81, v213
	v_mov_b32_e32 v74, v214
	v_mov_b32_e32 v75, v215
	v_mov_b32_e32 v76, v216
	v_mov_b32_e32 v77, v217
	v_mov_b32_e32 v70, v218
	v_mov_b32_e32 v71, v219
	v_mov_b32_e32 v72, v220
	v_mov_b32_e32 v73, v221
	v_mov_b32_e32 v66, v222
	v_mov_b32_e32 v67, v223
	v_mov_b32_e32 v68, v224
	v_mov_b32_e32 v69, v225
	v_cmp_lt_i32_e32 vcc, 7, v100
	s_and_saveexec_b64 s[2:3], vcc
	s_xor_b64 s[56:57], exec, s[2:3]
	s_cbranch_execz .LBB0_409
	s_movk_i32 s2, 0x200
	v_cmp_ne_u32_e32 vcc, s2, v168
	s_and_saveexec_b64 s[2:3], vcc
	s_xor_b64 s[2:3], exec, s[2:3]
	s_cbranch_execz .LBB0_406
	v_cmp_lt_u32_e32 vcc, 17, v100
	s_and_saveexec_b64 s[6:7], vcc
	s_xor_b64 s[62:63], exec, s[6:7]
	s_cbranch_execz .LBB0_403
	v_cmp_lt_u32_e32 vcc, 25, v100
	s_and_saveexec_b64 s[6:7], vcc
	s_xor_b64 s[64:65], exec, s[6:7]
	s_cbranch_execz .LBB0_400
	v_cmp_lt_u32_e32 vcc, 27, v100
	s_and_saveexec_b64 s[6:7], vcc
	s_xor_b64 s[66:67], exec, s[6:7]
	s_cbranch_execz .LBB0_397
	v_cmp_lt_u32_e32 vcc, 29, v100
	s_and_saveexec_b64 s[6:7], vcc
	s_xor_b64 s[68:69], exec, s[6:7]
	s_cbranch_execz .LBB0_394
	v_cmp_lt_u32_e32 vcc, 31, v100
	s_and_saveexec_b64 s[6:7], vcc
	s_xor_b64 s[70:71], exec, s[6:7]
	s_cbranch_execz .LBB0_391
	v_cmp_lt_u32_e32 vcc, 33, v100
	s_and_saveexec_b64 s[6:7], vcc
	s_xor_b64 s[72:73], exec, s[6:7]
	s_cbranch_execz .LBB0_388
	v_cmp_lt_u32_e32 vcc, 35, v100
	s_and_saveexec_b64 s[6:7], vcc
	s_xor_b64 s[58:59], exec, s[6:7]
	s_cbranch_execz .LBB0_385
	v_cmp_lt_u32_e32 vcc, 37, v100
	s_and_saveexec_b64 s[6:7], vcc
	s_xor_b64 s[22:23], exec, s[6:7]
	v_ashrrev_i32_e32 v171, 31, v170
	v_lshlrev_b64 v[100:101], 10, v[170:171]
	v_lshl_add_u64 v[100:101], s[38:39], 0, v[100:101]
	v_mov_b32_e32 v169, v1
	v_lshl_add_u64 v[100:101], v[168:169], 1, v[100:101]
	s_mov_b64 s[6:7], 0x4ffed80
	v_lshl_add_u64 v[102:103], v[100:101], 0, s[6:7]
	s_or_saveexec_b64 s[74:75], s[22:23]
	v_mov_b32_e32 v104, 0x200
	s_mov_b64 s[60:61], -1
	s_mov_b64 s[22:23], 0
	s_xor_b64 exec, exec, s[74:75]
	s_cbranch_execz .LBB0_384
	v_lshlrev_b32_e32 v0, 1, v172
	s_movk_i32 s6, 0xffdc
	v_add3_u32 v100, v100, v0, s6
	v_ashrrev_i32_e32 v101, 31, v100
	v_lshlrev_b64 v[100:101], 18, v[100:101]
	v_lshl_add_u64 v[100:101], s[10:11], 0, v[100:101]
	v_lshlrev_b32_e32 v0, 1, v200
	s_mov_b64 s[22:23], exec
	v_lshl_add_u64 v[102:103], v[100:101], 0, v[0:1]
	v_mov_b32_e32 v104, 0x800
	s_xor_b64 s[60:61], exec, -1

.LBB0_409:
	s_andn2_saveexec_b64 s[2:3], s[56:57]
	v_ashrrev_i32_e32 v171, 31, v170
	v_lshlrev_b64 v[100:101], 10, v[170:171]
	v_lshl_add_u64 v[100:101], s[50:51], 0, v[100:101]
	v_lshl_add_u64 v[100:101], v[168:169], 1, v[100:101]
	v_lshl_add_u64 v[102:103], v[100:101], 0, s[28:29]
	v_mov_b32_e32 v104, 0x200
	s_andn2_b64 s[60:61], s[60:61], exec
	s_or_b64 s[58:59], s[58:59], exec
	s_andn2_b64 s[22:23], s[22:23], exec
	s_or_b64 exec, exec, s[2:3]
	s_nop 0
	v_fmamk_f32 v0, v99, 0x3a800000, v208
	v_cmp_gt_f32_e32 vcc, s84, v0
	v_mul_f32_e32 v99, 0x4b800000, v0
	s_nop 0
	v_fmamk_f32 v98, v98, 0x3a800000, v208
	v_cndmask_b32_e32 v0, v0, v99, vcc
	v_rsq_f32_e32 v0, v0
	s_xor_b64 s[2:3], s[60:61], -1
	v_mul_f32_e32 v99, 0x45800000, v0
	v_cndmask_b32_e32 v0, v0, v99, vcc
	v_cmp_gt_f32_e32 vcc, s84, v98
	v_mul_f32_e32 v99, 0x4b800000, v98
	s_nop 0
	v_pk_fma_f32 v[100:101], v[52:53], v[0:1], v[96:97] op_sel_hi:[1,0,1]
	v_cndmask_b32_e32 v98, v98, v99, vcc
	v_rsq_f32_e32 v98, v98
	s_nop 0
	v_mul_f32_e32 v99, 0x45800000, v98
	v_cndmask_b32_e32 v106, v98, v99, vcc
	v_pk_fma_f32 v[98:99], v[50:51], v[0:1], v[94:95] op_sel_hi:[1,0,1]
	v_pk_fma_f32 v[50:51], v[34:35], v[106:107], v[94:95] op_sel_hi:[1,0,1]
	v_pk_fma_f32 v[52:53], v[36:37], v[106:107], v[96:97] op_sel_hi:[1,0,1]
	s_nop 0
	v_pk_fma_f32 v[94:95], v[54:55], v[0:1], v[90:91] op_sel_hi:[1,0,1]
	v_pk_fma_f32 v[38:39], v[38:39], v[106:107], v[90:91] op_sel_hi:[1,0,1]
	v_pk_fma_f32 v[96:97], v[56:57], v[0:1], v[92:93] op_sel_hi:[1,0,1]
	v_pk_fma_f32 v[40:41], v[40:41], v[106:107], v[92:93] op_sel_hi:[1,0,1]
	s_nop 0
	v_pk_fma_f32 v[54:55], v[58:59], v[0:1], v[86:87] op_sel_hi:[1,0,1]
	v_pk_fma_f32 v[34:35], v[42:43], v[106:107], v[86:87] op_sel_hi:[1,0,1]
	v_pk_fma_f32 v[56:57], v[60:61], v[0:1], v[88:89] op_sel_hi:[1,0,1]
	v_pk_fma_f32 v[36:37], v[44:45], v[106:107], v[88:89] op_sel_hi:[1,0,1]
	s_nop 0
	v_pk_fma_f32 v[58:59], v[62:63], v[0:1], v[82:83] op_sel_hi:[1,0,1]
	v_pk_fma_f32 v[42:43], v[46:47], v[106:107], v[82:83] op_sel_hi:[1,0,1]
	v_pk_fma_f32 v[46:47], v[64:65], v[0:1], v[84:85] op_sel_hi:[1,0,1]
	v_pk_fma_f32 v[44:45], v[48:49], v[106:107], v[84:85] op_sel_hi:[1,0,1]
	s_nop 0
	v_pk_fma_f32 v[62:63], v[18:19], v[0:1], v[78:79] op_sel_hi:[1,0,1]
	v_pk_fma_f32 v[18:19], v[2:3], v[106:107], v[78:79] op_sel_hi:[1,0,1]
	v_pk_fma_f32 v[64:65], v[20:21], v[0:1], v[80:81] op_sel_hi:[1,0,1]
	v_pk_fma_f32 v[20:21], v[4:5], v[106:107], v[80:81] op_sel_hi:[1,0,1]
	s_nop 0
	v_pk_fma_f32 v[48:49], v[22:23], v[0:1], v[74:75] op_sel_hi:[1,0,1]
	v_pk_fma_f32 v[6:7], v[6:7], v[106:107], v[74:75] op_sel_hi:[1,0,1]
	v_pk_fma_f32 v[60:61], v[24:25], v[0:1], v[76:77] op_sel_hi:[1,0,1]
	v_pk_fma_f32 v[8:9], v[8:9], v[106:107], v[76:77] op_sel_hi:[1,0,1]
	s_nop 0
	v_pk_fma_f32 v[24:25], v[26:27], v[0:1], v[70:71] op_sel_hi:[1,0,1]
	v_pk_fma_f32 v[2:3], v[10:11], v[106:107], v[70:71] op_sel_hi:[1,0,1]
	v_pk_fma_f32 v[26:27], v[28:29], v[0:1], v[72:73] op_sel_hi:[1,0,1]
	v_pk_fma_f32 v[4:5], v[12:13], v[106:107], v[72:73] op_sel_hi:[1,0,1]
	s_nop 0
	v_pk_fma_f32 v[22:23], v[30:31], v[0:1], v[66:67] op_sel_hi:[1,0,1]
	v_pk_fma_f32 v[10:11], v[14:15], v[106:107], v[66:67] op_sel_hi:[1,0,1]
	v_pk_fma_f32 v[14:15], v[32:33], v[0:1], v[68:69] op_sel_hi:[1,0,1]
	v_pk_fma_f32 v[12:13], v[16:17], v[106:107], v[68:69] op_sel_hi:[1,0,1]
	s_and_saveexec_b64 s[6:7], s[2:3]
	s_xor_b64 s[56:57], exec, s[6:7]
	s_cbranch_execz .LBB0_421
	s_xor_b64 s[2:3], s[58:59], -1
	s_and_saveexec_b64 s[6:7], s[2:3]
	s_xor_b64 s[2:3], exec, s[6:7]
	s_cbranch_execz .LBB0_418
	s_xor_b64 s[6:7], s[22:23], -1
	s_and_saveexec_b64 s[8:9], s[6:7]
	s_xor_b64 s[22:23], exec, s[8:9]
	s_cbranch_execz .LBB0_415
	s_movk_i32 s8, 0x60
	v_mad_i64_i32 v[2:3], s[6:7], v166, s8, v[194:195]
	v_or_b32_e32 v0, 32, v166
	global_store_dwordx4 v[2:3], v[98:101], off
	global_store_dwordx4 v[2:3], v[94:97], off offset:32
	global_store_dwordx4 v[2:3], v[54:57], off offset:64
	v_mad_i64_i32 v[2:3], s[6:7], v0, s8, v[194:195]
	global_store_dwordx4 v[2:3], v[50:53], off
	global_store_dwordx4 v[2:3], v[38:41], off offset:32
	global_store_dwordx4 v[2:3], v[34:37], off offset:64
